# pool-mixer GEMM epilogue: pool_scale vectors loaded once instead of re-loaded (with store-draining waits) for each of 16 row-group chunks; plus skinny_glu weight fragments up front
# speedup vs baseline: 1.0004x; 1.0004x over previous
; #define EPI_FOR_COLS _Pragma("unroll") for (int bj = 0; bj < 2; ++bj)
; __device__ __forceinline__ u32x4 pack8(const f32x4& a, const f32x4& b) { u32x4 w; w.x = pk2(a[0], a[1]); w.y = pk2(a[2], a[3]); w.z = pk2(b[0], b[1]); w.w = pk2(b[2], b[3]); return w; }
;     __device__ __forceinline__ bool operator()(EPI_ARGS) const {
;         asm volatile("" ::: "memory");
; #pragma unroll
;         for (int ai = 0; ai < 2; ++ai) {
;             u32x4 zw[4][2];
; #pragma unroll
;             for (int m = 0; m < 4; ++m) EPI_FOR_COLS { const int col = u.z * 256 + bj * 128 + wc * 32 + 8 * fq; zw[m][bj] = *(const u32x4*)(P + (size_t)EPI_ROW * NPROJ + C_PZ + col); }
;             __builtin_amdgcn_sched_barrier(0);
; #pragma unroll
;             for (int m = 0; m < 4; ++m) EPI_FOR_COLS { const int col = u.z * 256 + bj * 128 + wc * 32 + 8 * fq; float zf[8]; unpack8(zw[m][bj], zf);
;                 const f32x4 s0 = *(const f32x4*)(pscale + col), s1 = *(const f32x4*)(pscale + col + 4);
;                 f32x4 a = acc[ai][bj][m][0], b = acc[ai][bj][m][1];
; #pragma unroll
;                 for (int j = 0; j < 4; ++j) { a[j] = a[j] * s0[j] * zf[j]; b[j] = b[j] * s1[j] * zf[4 + j]; }
;                 *(u32x4*)(apool + (size_t)EPI_ROW * 1024 + col) = pack8(a, b); }
;             __builtin_amdgcn_sched_barrier(0);
;         }
.LBB0_1131:
	v_lshl_or_b32 v166, s77, 8, v182
	v_lshl_add_u32 v170, s81, 8, v180
	v_ashrrev_i32_e32 v167, 31, v166
	v_mov_b64_e32 v[172:173], s[44:45]
	v_mad_i64_i32 v[116:117], s[18:19], v170, s87, v[172:173]
	v_lshlrev_b64 v[168:169], 1, v[166:167]
	v_lshl_add_u64 v[116:117], v[116:117], 0, v[168:169]
	v_or_b32_e32 v178, 16, v170
	global_load_dwordx4 v[184:187], v[116:117], off offset:2048
	global_load_dwordx4 v[156:159], v[116:117], off offset:2304
	v_mad_i64_i32 v[116:117], s[18:19], v178, s87, v[172:173]
	v_lshl_add_u64 v[116:117], v[116:117], 0, v[168:169]
	v_or_b32_e32 v176, 32, v170
	global_load_dwordx4 v[152:155], v[116:117], off offset:2048
	global_load_dwordx4 v[148:151], v[116:117], off offset:2304
	v_mad_i64_i32 v[116:117], s[18:19], v176, s87, v[172:173]
	v_lshl_add_u64 v[116:117], v[116:117], 0, v[168:169]
	v_or_b32_e32 v174, 48, v170
	global_load_dwordx4 v[144:147], v[116:117], off offset:2048
	global_load_dwordx4 v[140:143], v[116:117], off offset:2304
	v_mad_i64_i32 v[116:117], s[18:19], v174, s87, v[172:173]
	v_lshl_add_u64 v[116:117], v[116:117], 0, v[168:169]
	global_load_dwordx4 v[128:131], v[116:117], off offset:2048
	s_nop 0
	global_load_dwordx4 v[116:119], v[116:117], off offset:2304
	v_ashrrev_i32_e32 v171, 31, v170
	v_ashrrev_i32_e32 v179, 31, v178
	v_ashrrev_i32_e32 v177, 31, v176
	v_ashrrev_i32_e32 v175, 31, v174
	v_lshl_add_u64 v[166:167], v[166:167], 2, s[50:51]
	global_load_dwordx4 v[222:225], v[166:167], off offset:16
	global_load_dwordx4 v[226:229], v[166:167], off
	global_load_dwordx4 v[242:245], v[166:167], off offset:528
	global_load_dwordx4 v[246:249], v[166:167], off offset:512
	s_waitcnt vmcnt(0)
	v_lshlrev_b32_e32 v200, 16, v184
	v_and_b32_e32 v201, 0xffff0000, v184
	v_lshlrev_b64 v[198:199], 11, v[170:171]
	v_pk_mul_f32 v[132:133], v[132:133], v[222:223]
	v_pk_mul_f32 v[136:137], v[136:137], v[226:227]
	v_lshlrev_b32_e32 v192, 16, v186
	v_and_b32_e32 v193, 0xffff0000, v186
	v_pk_mul_f32 v[138:139], v[138:139], v[228:229]
	v_pk_mul_f32 v[188:189], v[132:133], v[192:193]
	v_lshlrev_b32_e32 v132, 16, v185
	v_and_b32_e32 v133, 0xffff0000, v185
	v_pk_mul_f32 v[136:137], v[136:137], v[200:201]
	v_pk_mul_f32 v[134:135], v[134:135], v[224:225]
	v_pk_mul_f32 v[138:139], v[138:139], v[132:133]
	v_lshlrev_b32_e32 v132, 16, v187
	v_and_b32_e32 v133, 0xffff0000, v187
	v_pk_mul_f32 v[184:185], v[134:135], v[132:133]
	v_cvt_pk_bf16_f32 v132, v136, v137
	v_lshl_add_u64 v[136:137], s[48:49], 0, v[198:199]
	v_cvt_pk_bf16_f32 v133, v138, v139
	v_cvt_pk_bf16_f32 v134, v188, v189
	v_cvt_pk_bf16_f32 v135, v184, v185
	v_lshl_add_u64 v[184:185], v[136:137], 0, v[168:169]
	global_store_dwordx4 v[184:185], v[132:135], off
	s_nop 0
	v_lshlrev_b32_e32 v186, 16, v156
	v_and_b32_e32 v187, 0xffff0000, v156
	v_pk_mul_f32 v[120:121], v[120:121], v[242:243]
	v_pk_mul_f32 v[124:125], v[124:125], v[246:247]
	v_lshlrev_b32_e32 v136, 16, v158
	v_and_b32_e32 v137, 0xffff0000, v158
	v_pk_mul_f32 v[126:127], v[126:127], v[248:249]
	v_pk_mul_f32 v[132:133], v[120:121], v[136:137]
	v_lshlrev_b32_e32 v120, 16, v157
	v_and_b32_e32 v121, 0xffff0000, v157
	v_pk_mul_f32 v[122:123], v[122:123], v[244:245]
	v_pk_mul_f32 v[126:127], v[126:127], v[120:121]
	v_lshlrev_b32_e32 v120, 16, v159
	v_and_b32_e32 v121, 0xffff0000, v159
	v_pk_mul_f32 v[124:125], v[124:125], v[186:187]
	v_pk_mul_f32 v[134:135], v[122:123], v[120:121]
	v_cvt_pk_bf16_f32 v120, v124, v125
	v_cvt_pk_bf16_f32 v121, v126, v127
	v_cvt_pk_bf16_f32 v122, v132, v133
	v_cvt_pk_bf16_f32 v123, v134, v135
	global_store_dwordx4 v[184:185], v[120:123], off offset:256
	s_nop 0
	v_lshlrev_b32_e32 v134, 16, v152
	v_and_b32_e32 v135, 0xffff0000, v152
	v_lshlrev_b64 v[132:133], 11, v[178:179]
	v_pk_mul_f32 v[108:109], v[108:109], v[222:223]
	v_pk_mul_f32 v[112:113], v[112:113], v[226:227]
	v_lshlrev_b32_e32 v124, 16, v154
	v_and_b32_e32 v125, 0xffff0000, v154
	v_pk_mul_f32 v[114:115], v[114:115], v[228:229]
	v_pk_mul_f32 v[120:121], v[108:109], v[124:125]
	v_lshlrev_b32_e32 v108, 16, v153
	v_and_b32_e32 v109, 0xffff0000, v153
	v_pk_mul_f32 v[112:113], v[112:113], v[134:135]
	v_pk_mul_f32 v[110:111], v[110:111], v[224:225]
	v_pk_mul_f32 v[114:115], v[114:115], v[108:109]
	v_lshlrev_b32_e32 v108, 16, v155
	v_and_b32_e32 v109, 0xffff0000, v155
	v_pk_mul_f32 v[122:123], v[110:111], v[108:109]
	v_cvt_pk_bf16_f32 v108, v112, v113
	v_lshl_add_u64 v[112:113], s[48:49], 0, v[132:133]
	v_cvt_pk_bf16_f32 v109, v114, v115
	v_cvt_pk_bf16_f32 v110, v120, v121
	v_cvt_pk_bf16_f32 v111, v122, v123
	v_lshl_add_u64 v[120:121], v[112:113], 0, v[168:169]
	global_store_dwordx4 v[120:121], v[108:111], off
	s_nop 0
	v_lshlrev_b32_e32 v122, 16, v148
	v_and_b32_e32 v123, 0xffff0000, v148
	v_pk_mul_f32 v[100:101], v[100:101], v[242:243]
	v_pk_mul_f32 v[104:105], v[104:105], v[246:247]
	v_lshlrev_b32_e32 v112, 16, v150
	v_and_b32_e32 v113, 0xffff0000, v150
	v_pk_mul_f32 v[106:107], v[106:107], v[248:249]
	v_pk_mul_f32 v[108:109], v[100:101], v[112:113]
	v_lshlrev_b32_e32 v100, 16, v149
	v_and_b32_e32 v101, 0xffff0000, v149
	v_pk_mul_f32 v[102:103], v[102:103], v[244:245]
	v_pk_mul_f32 v[106:107], v[106:107], v[100:101]
	v_lshlrev_b32_e32 v100, 16, v151
	v_and_b32_e32 v101, 0xffff0000, v151
	v_pk_mul_f32 v[104:105], v[104:105], v[122:123]
	v_pk_mul_f32 v[110:111], v[102:103], v[100:101]
	v_cvt_pk_bf16_f32 v100, v104, v105
	v_cvt_pk_bf16_f32 v101, v106, v107
	v_cvt_pk_bf16_f32 v102, v108, v109
	v_cvt_pk_bf16_f32 v103, v110, v111
	global_store_dwordx4 v[120:121], v[100:103], off offset:256
	s_nop 0
	v_lshlrev_b32_e32 v110, 16, v144
	v_and_b32_e32 v111, 0xffff0000, v144
	v_lshlrev_b64 v[108:109], 11, v[176:177]
; #define EPI_FOR_COLS _Pragma("unroll") for (int bj = 0; bj < 2; ++bj)
; __device__ __forceinline__ u32x4 pack8(const f32x4& a, const f32x4& b) { u32x4 w; w.x = pk2(a[0], a[1]); w.y = pk2(a[2], a[3]); w.z = pk2(b[0], b[1]); w.w = pk2(b[2], b[3]); return w; }
;     __device__ __forceinline__ bool operator()(EPI_ARGS) const {
;     ...
;         for (int ai = 0; ai < 2; ++ai) {
;             u32x4 zw[4][2];
; #pragma unroll
;             for (int m = 0; m < 4; ++m) EPI_FOR_COLS { const int col = u.z * 256 + bj * 128 + wc * 32 + 8 * fq; zw[m][bj] = *(const u32x4*)(P + (size_t)EPI_ROW * NPROJ + C_PZ + col); }
;             __builtin_amdgcn_sched_barrier(0);
; #pragma unroll
;             for (int m = 0; m < 4; ++m) EPI_FOR_COLS { const int col = u.z * 256 + bj * 128 + wc * 32 + 8 * fq; float zf[8]; unpack8(zw[m][bj], zf);
;                 const f32x4 s0 = *(const f32x4*)(pscale + col), s1 = *(const f32x4*)(pscale + col + 4);
;                 f32x4 a = acc[ai][bj][m][0], b = acc[ai][bj][m][1];
; #pragma unroll
;                 for (int j = 0; j < 4; ++j) { a[j] = a[j] * s0[j] * zf[j]; b[j] = b[j] * s1[j] * zf[4 + j]; }
;                 *(u32x4*)(apool + (size_t)EPI_ROW * 1024 + col) = pack8(a, b); }
;             __builtin_amdgcn_sched_barrier(0);
;         }
	v_pk_mul_f32 v[90:91], v[90:91], v[222:223]
	v_pk_mul_f32 v[94:95], v[94:95], v[226:227]
	v_lshlrev_b32_e32 v104, 16, v146
	v_and_b32_e32 v105, 0xffff0000, v146
	v_pk_mul_f32 v[96:97], v[96:97], v[228:229]
	v_pk_mul_f32 v[100:101], v[90:91], v[104:105]
	v_lshlrev_b32_e32 v90, 16, v145
	v_and_b32_e32 v91, 0xffff0000, v145
	v_pk_mul_f32 v[94:95], v[94:95], v[110:111]
	v_pk_mul_f32 v[92:93], v[92:93], v[224:225]
	v_pk_mul_f32 v[96:97], v[96:97], v[90:91]
	v_lshlrev_b32_e32 v90, 16, v147
	v_and_b32_e32 v91, 0xffff0000, v147
	v_pk_mul_f32 v[102:103], v[92:93], v[90:91]
	v_cvt_pk_bf16_f32 v90, v94, v95
	v_lshl_add_u64 v[94:95], s[48:49], 0, v[108:109]
	v_cvt_pk_bf16_f32 v91, v96, v97
	v_cvt_pk_bf16_f32 v92, v100, v101
	v_cvt_pk_bf16_f32 v93, v102, v103
	v_lshl_add_u64 v[100:101], v[94:95], 0, v[168:169]
	global_store_dwordx4 v[100:101], v[90:93], off
	s_nop 0
	v_lshlrev_b32_e32 v102, 16, v140
	v_and_b32_e32 v103, 0xffff0000, v140
	v_pk_mul_f32 v[82:83], v[82:83], v[242:243]
	v_pk_mul_f32 v[86:87], v[86:87], v[246:247]
	v_lshlrev_b32_e32 v94, 16, v142
	v_and_b32_e32 v95, 0xffff0000, v142
	v_pk_mul_f32 v[88:89], v[88:89], v[248:249]
	v_pk_mul_f32 v[90:91], v[82:83], v[94:95]
	v_lshlrev_b32_e32 v82, 16, v141
	v_and_b32_e32 v83, 0xffff0000, v141
	v_pk_mul_f32 v[84:85], v[84:85], v[244:245]
	v_pk_mul_f32 v[88:89], v[88:89], v[82:83]
	v_lshlrev_b32_e32 v82, 16, v143
	v_and_b32_e32 v83, 0xffff0000, v143
	v_pk_mul_f32 v[86:87], v[86:87], v[102:103]
	v_pk_mul_f32 v[92:93], v[84:85], v[82:83]
	v_cvt_pk_bf16_f32 v82, v86, v87
	v_cvt_pk_bf16_f32 v83, v88, v89
	v_cvt_pk_bf16_f32 v84, v90, v91
	v_cvt_pk_bf16_f32 v85, v92, v93
	global_store_dwordx4 v[100:101], v[82:85], off offset:256
	s_nop 0
	v_lshlrev_b32_e32 v92, 16, v128
	v_and_b32_e32 v93, 0xffff0000, v128
	v_lshlrev_b64 v[90:91], 11, v[174:175]
	v_pk_mul_f32 v[74:75], v[74:75], v[222:223]
	v_pk_mul_f32 v[78:79], v[78:79], v[226:227]
	v_lshlrev_b32_e32 v86, 16, v130
	v_and_b32_e32 v87, 0xffff0000, v130
	v_pk_mul_f32 v[80:81], v[80:81], v[228:229]
	v_pk_mul_f32 v[82:83], v[74:75], v[86:87]
	v_lshlrev_b32_e32 v74, 16, v129
	v_and_b32_e32 v75, 0xffff0000, v129
	v_pk_mul_f32 v[78:79], v[78:79], v[92:93]
	v_pk_mul_f32 v[76:77], v[76:77], v[224:225]
	v_pk_mul_f32 v[80:81], v[80:81], v[74:75]
	v_lshlrev_b32_e32 v74, 16, v131
	v_and_b32_e32 v75, 0xffff0000, v131
	v_pk_mul_f32 v[84:85], v[76:77], v[74:75]
	v_cvt_pk_bf16_f32 v74, v78, v79
	v_lshl_add_u64 v[78:79], s[48:49], 0, v[90:91]
	v_cvt_pk_bf16_f32 v75, v80, v81
	v_cvt_pk_bf16_f32 v76, v82, v83
	v_cvt_pk_bf16_f32 v77, v84, v85
	v_lshl_add_u64 v[82:83], v[78:79], 0, v[168:169]
	global_store_dwordx4 v[82:83], v[74:77], off
	s_nop 0
	v_lshlrev_b32_e32 v84, 16, v116
	v_and_b32_e32 v85, 0xffff0000, v116
	v_pk_mul_f32 v[66:67], v[66:67], v[242:243]
	v_pk_mul_f32 v[70:71], v[70:71], v[246:247]
	v_lshlrev_b32_e32 v78, 16, v118
	v_and_b32_e32 v79, 0xffff0000, v118
	v_pk_mul_f32 v[72:73], v[72:73], v[248:249]
	v_pk_mul_f32 v[74:75], v[66:67], v[78:79]
	v_lshlrev_b32_e32 v66, 16, v117
	v_and_b32_e32 v67, 0xffff0000, v117
	v_pk_mul_f32 v[68:69], v[68:69], v[244:245]
	v_pk_mul_f32 v[72:73], v[72:73], v[66:67]
	v_lshlrev_b32_e32 v66, 16, v119
	v_and_b32_e32 v67, 0xffff0000, v119
	v_pk_mul_f32 v[70:71], v[70:71], v[84:85]
	v_pk_mul_f32 v[76:77], v[68:69], v[66:67]
	v_cvt_pk_bf16_f32 v66, v70, v71
	v_cvt_pk_bf16_f32 v67, v72, v73
	v_cvt_pk_bf16_f32 v68, v74, v75
	v_cvt_pk_bf16_f32 v69, v76, v77
	global_store_dwordx4 v[82:83], v[66:69], off offset:256
	v_add_u32_e32 v106, 0x80, v170
	s_nop 0
	v_mad_i64_i32 v[66:67], s[18:19], v106, s87, v[172:173]
	v_lshl_add_u64 v[66:67], v[66:67], 0, v[168:169]
	v_add_u32_e32 v100, 0x90, v170
	global_load_dwordx4 v[102:105], v[66:67], off offset:2048
	global_load_dwordx4 v[90:93], v[66:67], off offset:2304
	v_mad_i64_i32 v[66:67], s[18:19], v100, s87, v[172:173]
	v_lshl_add_u64 v[66:67], v[66:67], 0, v[168:169]
	v_add_u32_e32 v96, 0xa0, v170
	global_load_dwordx4 v[86:89], v[66:67], off offset:2048
	global_load_dwordx4 v[82:85], v[66:67], off offset:2304
	v_mad_i64_i32 v[66:67], s[18:19], v96, s87, v[172:173]
	v_lshl_add_u64 v[66:67], v[66:67], 0, v[168:169]
	v_add_u32_e32 v94, 0xb0, v170
	global_load_dwordx4 v[78:81], v[66:67], off offset:2048
	global_load_dwordx4 v[74:77], v[66:67], off offset:2304
	v_mad_i64_i32 v[66:67], s[18:19], v94, s87, v[172:173]
	v_lshl_add_u64 v[66:67], v[66:67], 0, v[168:169]
	global_load_dwordx4 v[70:73], v[66:67], off offset:2048
	s_nop 0
	global_load_dwordx4 v[66:69], v[66:67], off offset:2304
	v_ashrrev_i32_e32 v107, 31, v106
	v_ashrrev_i32_e32 v101, 31, v100
	v_ashrrev_i32_e32 v97, 31, v96
	v_ashrrev_i32_e32 v95, 31, v94
	v_lshlrev_b64 v[114:115], 11, v[106:107]
	s_waitcnt vmcnt(7)
	v_lshlrev_b32_e32 v116, 16, v102
	v_and_b32_e32 v117, 0xffff0000, v102
	v_pk_mul_f32 v[58:59], v[58:59], v[222:223]
	s_waitcnt vmcnt(0)
; #define EPI_FOR_COLS _Pragma("unroll") for (int bj = 0; bj < 2; ++bj)
; __device__ __forceinline__ u32x4 pack8(const f32x4& a, const f32x4& b) { u32x4 w; w.x = pk2(a[0], a[1]); w.y = pk2(a[2], a[3]); w.z = pk2(b[0], b[1]); w.w = pk2(b[2], b[3]); return w; }
;     __device__ __forceinline__ bool operator()(EPI_ARGS) const {
;     ...
;             for (int m = 0; m < 4; ++m) EPI_FOR_COLS { const int col = u.z * 256 + bj * 128 + wc * 32 + 8 * fq; float zf[8]; unpack8(zw[m][bj], zf);
;                 const f32x4 s0 = *(const f32x4*)(pscale + col), s1 = *(const f32x4*)(pscale + col + 4);
;                 f32x4 a = acc[ai][bj][m][0], b = acc[ai][bj][m][1];
; #pragma unroll
;                 for (int j = 0; j < 4; ++j) { a[j] = a[j] * s0[j] * zf[j]; b[j] = b[j] * s1[j] * zf[4 + j]; }
;                 *(u32x4*)(apool + (size_t)EPI_ROW * 1024 + col) = pack8(a, b); }
;             __builtin_amdgcn_sched_barrier(0);
	v_pk_mul_f32 v[62:63], v[62:63], v[226:227]
	v_lshlrev_b32_e32 v110, 16, v104
	v_and_b32_e32 v111, 0xffff0000, v104
	v_pk_mul_f32 v[64:65], v[64:65], v[228:229]
	v_pk_mul_f32 v[106:107], v[58:59], v[110:111]
	v_lshlrev_b32_e32 v58, 16, v103
	v_and_b32_e32 v59, 0xffff0000, v103
	v_pk_mul_f32 v[62:63], v[62:63], v[116:117]
	v_pk_mul_f32 v[60:61], v[60:61], v[224:225]
	v_pk_mul_f32 v[64:65], v[64:65], v[58:59]
	v_lshlrev_b32_e32 v58, 16, v105
	v_and_b32_e32 v59, 0xffff0000, v105
	v_pk_mul_f32 v[102:103], v[60:61], v[58:59]
	v_cvt_pk_bf16_f32 v58, v62, v63
	v_lshl_add_u64 v[62:63], s[48:49], 0, v[114:115]
	v_cvt_pk_bf16_f32 v59, v64, v65
	v_cvt_pk_bf16_f32 v60, v106, v107
	v_cvt_pk_bf16_f32 v61, v102, v103
	v_lshl_add_u64 v[102:103], v[62:63], 0, v[168:169]
	global_store_dwordx4 v[102:103], v[58:61], off
	s_nop 0
	v_lshlrev_b32_e32 v104, 16, v90
	v_and_b32_e32 v105, 0xffff0000, v90
	v_pk_mul_f32 v[50:51], v[50:51], v[242:243]
	v_pk_mul_f32 v[54:55], v[54:55], v[246:247]
	v_lshlrev_b32_e32 v62, 16, v92
	v_and_b32_e32 v63, 0xffff0000, v92
	v_pk_mul_f32 v[56:57], v[56:57], v[248:249]
	v_pk_mul_f32 v[58:59], v[50:51], v[62:63]
	v_lshlrev_b32_e32 v50, 16, v91
	v_and_b32_e32 v51, 0xffff0000, v91
	v_pk_mul_f32 v[52:53], v[52:53], v[244:245]
	v_pk_mul_f32 v[56:57], v[56:57], v[50:51]
	v_lshlrev_b32_e32 v50, 16, v93
	v_and_b32_e32 v51, 0xffff0000, v93
	v_pk_mul_f32 v[54:55], v[54:55], v[104:105]
	v_pk_mul_f32 v[60:61], v[52:53], v[50:51]
	v_cvt_pk_bf16_f32 v50, v54, v55
	v_cvt_pk_bf16_f32 v51, v56, v57
	v_cvt_pk_bf16_f32 v52, v58, v59
	v_cvt_pk_bf16_f32 v53, v60, v61
	global_store_dwordx4 v[102:103], v[50:53], off offset:256
	s_nop 0
	v_lshlrev_b32_e32 v60, 16, v86
	v_and_b32_e32 v61, 0xffff0000, v86
	v_lshlrev_b64 v[58:59], 11, v[100:101]
	v_pk_mul_f32 v[42:43], v[42:43], v[222:223]
	v_pk_mul_f32 v[46:47], v[46:47], v[226:227]
	v_lshlrev_b32_e32 v54, 16, v88
	v_and_b32_e32 v55, 0xffff0000, v88
	v_pk_mul_f32 v[48:49], v[48:49], v[228:229]
	v_pk_mul_f32 v[50:51], v[42:43], v[54:55]
	v_lshlrev_b32_e32 v42, 16, v87
	v_and_b32_e32 v43, 0xffff0000, v87
	v_pk_mul_f32 v[46:47], v[46:47], v[60:61]
	v_pk_mul_f32 v[44:45], v[44:45], v[224:225]
	v_pk_mul_f32 v[48:49], v[48:49], v[42:43]
	v_lshlrev_b32_e32 v42, 16, v89
	v_and_b32_e32 v43, 0xffff0000, v89
	v_pk_mul_f32 v[52:53], v[44:45], v[42:43]
	v_cvt_pk_bf16_f32 v42, v46, v47
	v_lshl_add_u64 v[46:47], s[48:49], 0, v[58:59]
	v_cvt_pk_bf16_f32 v43, v48, v49
	v_cvt_pk_bf16_f32 v44, v50, v51
	v_cvt_pk_bf16_f32 v45, v52, v53
	v_lshl_add_u64 v[50:51], v[46:47], 0, v[168:169]
	global_store_dwordx4 v[50:51], v[42:45], off
	s_nop 0
	v_lshlrev_b32_e32 v52, 16, v82
	v_and_b32_e32 v53, 0xffff0000, v82
	v_pk_mul_f32 v[34:35], v[34:35], v[242:243]
	v_pk_mul_f32 v[38:39], v[38:39], v[246:247]
	v_lshlrev_b32_e32 v46, 16, v84
	v_and_b32_e32 v47, 0xffff0000, v84
	v_pk_mul_f32 v[40:41], v[40:41], v[248:249]
	v_pk_mul_f32 v[42:43], v[34:35], v[46:47]
	v_lshlrev_b32_e32 v34, 16, v83
	v_and_b32_e32 v35, 0xffff0000, v83
	v_pk_mul_f32 v[36:37], v[36:37], v[244:245]
	v_pk_mul_f32 v[40:41], v[40:41], v[34:35]
	v_lshlrev_b32_e32 v34, 16, v85
	v_and_b32_e32 v35, 0xffff0000, v85
	v_pk_mul_f32 v[38:39], v[38:39], v[52:53]
	v_pk_mul_f32 v[44:45], v[36:37], v[34:35]
	v_cvt_pk_bf16_f32 v34, v38, v39
	v_cvt_pk_bf16_f32 v35, v40, v41
	v_cvt_pk_bf16_f32 v36, v42, v43
	v_cvt_pk_bf16_f32 v37, v44, v45
	global_store_dwordx4 v[50:51], v[34:37], off offset:256
	s_nop 0
	v_lshlrev_b32_e32 v44, 16, v78
	v_and_b32_e32 v45, 0xffff0000, v78
	v_lshlrev_b64 v[42:43], 11, v[96:97]
	v_pk_mul_f32 v[26:27], v[26:27], v[222:223]
	v_pk_mul_f32 v[30:31], v[30:31], v[226:227]
	v_lshlrev_b32_e32 v38, 16, v80
	v_and_b32_e32 v39, 0xffff0000, v80
	v_pk_mul_f32 v[32:33], v[32:33], v[228:229]
	v_pk_mul_f32 v[34:35], v[26:27], v[38:39]
	v_lshlrev_b32_e32 v26, 16, v79
	v_and_b32_e32 v27, 0xffff0000, v79
	v_pk_mul_f32 v[30:31], v[30:31], v[44:45]
	v_pk_mul_f32 v[28:29], v[28:29], v[224:225]
	v_pk_mul_f32 v[32:33], v[32:33], v[26:27]
	v_lshlrev_b32_e32 v26, 16, v81
	v_and_b32_e32 v27, 0xffff0000, v81
	v_pk_mul_f32 v[36:37], v[28:29], v[26:27]
	v_cvt_pk_bf16_f32 v26, v30, v31
	v_lshl_add_u64 v[30:31], s[48:49], 0, v[42:43]
	v_cvt_pk_bf16_f32 v27, v32, v33
	v_cvt_pk_bf16_f32 v28, v34, v35
	v_cvt_pk_bf16_f32 v29, v36, v37
	v_lshl_add_u64 v[34:35], v[30:31], 0, v[168:169]
	global_store_dwordx4 v[34:35], v[26:29], off
	s_nop 0
	v_lshlrev_b32_e32 v36, 16, v74
	v_and_b32_e32 v37, 0xffff0000, v74
	v_pk_mul_f32 v[18:19], v[18:19], v[242:243]
	v_pk_mul_f32 v[22:23], v[22:23], v[246:247]
	v_lshlrev_b32_e32 v30, 16, v76
	v_and_b32_e32 v31, 0xffff0000, v76
	v_pk_mul_f32 v[24:25], v[24:25], v[248:249]
	v_pk_mul_f32 v[26:27], v[18:19], v[30:31]
	v_lshlrev_b32_e32 v18, 16, v75
	v_and_b32_e32 v19, 0xffff0000, v75
	v_pk_mul_f32 v[20:21], v[20:21], v[244:245]
	v_pk_mul_f32 v[24:25], v[24:25], v[18:19]
	v_lshlrev_b32_e32 v18, 16, v77
	v_and_b32_e32 v19, 0xffff0000, v77
	v_pk_mul_f32 v[22:23], v[22:23], v[36:37]
	v_pk_mul_f32 v[28:29], v[20:21], v[18:19]
	v_cvt_pk_bf16_f32 v18, v22, v23
	v_cvt_pk_bf16_f32 v19, v24, v25
	v_cvt_pk_bf16_f32 v20, v26, v27
	v_cvt_pk_bf16_f32 v21, v28, v29
	global_store_dwordx4 v[34:35], v[18:21], off offset:256
	s_nop 0
	v_lshlrev_b32_e32 v28, 16, v70
	v_and_b32_e32 v29, 0xffff0000, v70
	v_lshlrev_b64 v[26:27], 11, v[94:95]
	v_pk_mul_f32 v[10:11], v[10:11], v[222:223]
	v_pk_mul_f32 v[14:15], v[14:15], v[226:227]
	v_lshlrev_b32_e32 v22, 16, v72
	v_and_b32_e32 v23, 0xffff0000, v72
	v_pk_mul_f32 v[16:17], v[16:17], v[228:229]
	v_pk_mul_f32 v[18:19], v[10:11], v[22:23]
	v_lshlrev_b32_e32 v10, 16, v71
	v_and_b32_e32 v11, 0xffff0000, v71
	v_pk_mul_f32 v[14:15], v[14:15], v[28:29]
	v_pk_mul_f32 v[12:13], v[12:13], v[224:225]
	v_pk_mul_f32 v[16:17], v[16:17], v[10:11]
	v_lshlrev_b32_e32 v10, 16, v73
	v_and_b32_e32 v11, 0xffff0000, v73
	v_pk_mul_f32 v[20:21], v[12:13], v[10:11]
	v_cvt_pk_bf16_f32 v10, v14, v15
	v_lshl_add_u64 v[14:15], s[48:49], 0, v[26:27]
	v_cvt_pk_bf16_f32 v11, v16, v17
	v_cvt_pk_bf16_f32 v12, v18, v19
	v_cvt_pk_bf16_f32 v13, v20, v21
	v_lshl_add_u64 v[18:19], v[14:15], 0, v[168:169]
	global_store_dwordx4 v[18:19], v[10:13], off
	s_nop 0
	v_lshlrev_b32_e32 v20, 16, v66
	v_and_b32_e32 v21, 0xffff0000, v66
	v_pk_mul_f32 v[2:3], v[2:3], v[242:243]
	v_pk_mul_f32 v[6:7], v[6:7], v[246:247]
	v_lshlrev_b32_e32 v14, 16, v68
	v_and_b32_e32 v15, 0xffff0000, v68
	v_pk_mul_f32 v[8:9], v[8:9], v[248:249]
	v_pk_mul_f32 v[10:11], v[2:3], v[14:15]
	v_lshlrev_b32_e32 v2, 16, v67
	v_and_b32_e32 v3, 0xffff0000, v67
	v_pk_mul_f32 v[4:5], v[4:5], v[244:245]
	v_pk_mul_f32 v[8:9], v[8:9], v[2:3]
	v_lshlrev_b32_e32 v2, 16, v69
	v_and_b32_e32 v3, 0xffff0000, v69
	v_pk_mul_f32 v[6:7], v[6:7], v[20:21]
	v_pk_mul_f32 v[12:13], v[4:5], v[2:3]
	v_cvt_pk_bf16_f32 v2, v6, v7
	v_cvt_pk_bf16_f32 v3, v8, v9
	v_cvt_pk_bf16_f32 v4, v10, v11
	v_cvt_pk_bf16_f32 v5, v12, v13
	global_store_dwordx4 v[18:19], v[2:5], off offset:256
	s_andn2_b64 vcc, exec, s[42:43]
	s_cbranch_vccnz .LBB0_1120
; #define PG8_BAR __builtin_amdgcn_s_barrier()
; template <class Epi, class Sched>
; __device__ __forceinline__ void gemm_phase(LAS unsigned char* lds, const Gemm g, const Sched& S, const Epi& E) {
;     ...
;         if (!has_next) break;
;         if (!keep) {
; #pragma unroll
;             for (int a = 0; a < 2; ++a)
; #pragma unroll
;                 for (int b = 0; b < 2; ++b)
; #pragma unroll
;                     for (int m = 0; m < 4; ++m)
; #pragma unroll
;                         for (int n = 0; n < 2; ++n) acc[a][b][m][n] = (f32x4){0.f, 0.f, 0.f, 0.f};
;         }
;         cur = nxt; cA = nA; cB = nB; ++ui;
;         if (wr == 1) PG8_BAR;
	v_readlane_b32 s18, v255, 16
	v_readlane_b32 s19, v255, 17
	s_andn2_b64 vcc, exec, s[18:19]
	s_cbranch_vccnz .LBB0_1119
	s_barrier
	s_branch .LBB0_1119
